# v22: v15 + run-time reciprocal seed of the tile-index division in the six unit headers replaced by its constant (group size is always 8); quotient bit-identical
# speedup vs baseline: 1.0052x; 1.0052x over previous
.LBB0_266:
	s_add_i32 s61, s61, 1
	s_mul_i32 s0, s61, s75
	s_mul_hi_u32 s1, s61, s74
	s_add_i32 s1, s1, s0
	s_mul_i32 s0, s61, s74
	s_add_u32 s40, s0, s85
	s_addc_u32 s41, s1, s62
	v_cmp_gt_i64_e32 vcc, s[40:41], v[170:171]
	v_cmp_lt_i64_e64 s[4:5], s[40:41], v[168:169]
	s_cbranch_vccnz .LBB0_268
	s_ashr_i32 s0, s40, 31
	s_lshr_b32 s0, s0, 29
	s_add_i32 s0, s40, s0
	s_ashr_i32 s1, s0, 3
	s_and_b32 s0, s0, -8
	s_sub_i32 s0, s40, s0
	s_cmp_lt_i32 s0, 0
	s_movk_i32 s7, 0xe1
	s_cselect_b32 s7, s7, 0xe0
	s_mul_i32 s0, s0, s7
	s_add_i32 s0, s0, s1
	s_mul_hi_i32 s1, s0, 0x92492493
	s_add_i32 s1, s1, s0
	s_lshr_b32 s7, s1, 31
	s_ashr_i32 s1, s1, 8
	s_add_i32 s1, s1, s7
	s_lshl_b32 s7, s1, 3
	s_sub_i32 s11, 32, s7
	s_min_i32 s11, s11, 8
	s_abs_i32 s33, s11
	s_sub_i32 s37, 0, s33
	s_mulk_i32 s1, 0x1c0
	s_sub_i32 s0, s0, s1
	s_abs_i32 s1, s0
	s_xor_b32 s36, s0, s11
	s_ashr_i32 s36, s36, 31
	s_mov_b32 s38, 0x1fffffc0
	s_mul_i32 s37, s37, s38
	s_mul_hi_u32 s37, s38, s37
	s_add_i32 s38, s38, s37
	s_mul_hi_u32 s37, s1, s38
	s_mul_i32 s38, s37, s33
	s_sub_i32 s1, s1, s38
	s_add_i32 s39, s37, 1
	s_sub_i32 s38, s1, s33
	s_cmp_ge_u32 s1, s33
	s_cselect_b32 s37, s39, s37
	s_cselect_b32 s1, s38, s1
	s_add_i32 s38, s37, 1
	s_cmp_ge_u32 s1, s33
	s_cselect_b32 s1, s38, s37
	s_xor_b32 s1, s1, s36
	s_sub_i32 s36, s1, s36
	s_mul_i32 s1, s36, s11
	s_sub_i32 s0, s0, s1
	s_add_i32 s38, s7, s0

.LBB0_337:
	s_ashr_i32 s0, s0, 3
	s_add_i32 s0, s27, s0
	s_ashr_i32 s24, s0, 31
	s_lshr_b32 s24, s24, 26
	s_add_i32 s24, s0, s24
	s_ashr_i32 s25, s24, 6
	s_lshl_b32 s25, s25, 3
	s_sub_i32 s26, 32, s25
	s_min_i32 s26, s26, 8
	s_abs_i32 s27, s26
	s_sub_i32 s29, 0, s27
	s_andn2_b32 s24, s24, 63
	s_sub_i32 s0, s0, s24
	s_abs_i32 s24, s0
	s_xor_b32 s28, s0, s26
	s_ashr_i32 s28, s28, 31
	s_mov_b32 s30, 0x1fffffc0
	s_mul_i32 s29, s29, s30
	s_mul_hi_u32 s29, s30, s29
	s_add_i32 s30, s30, s29
	s_mul_hi_u32 s29, s24, s30
	s_mul_i32 s30, s29, s27
	s_sub_i32 s24, s24, s30
	s_add_i32 s31, s29, 1
	s_sub_i32 s30, s24, s27
	s_cmp_ge_u32 s24, s27
	s_cselect_b32 s29, s31, s29
	s_cselect_b32 s24, s30, s24
	s_add_i32 s30, s29, 1
	s_cmp_ge_u32 s24, s27
	s_cselect_b32 s24, s30, s29
	s_xor_b32 s24, s24, s28
	s_sub_i32 s24, s24, s28
	s_mul_i32 s26, s24, s26
	s_sub_i32 s0, s0, s26
	s_add_i32 s26, s25, s0

.LBB0_1340:
	s_ashr_i32 s0, s0, 3
	s_add_i32 s0, s22, s0
	s_ashr_i32 s5, s0, 31
	s_lshr_b32 s5, s5, 24
	s_add_i32 s5, s0, s5
	s_ashr_i32 s20, s5, 8
	s_lshl_b32 s21, s20, 3
	s_sub_i32 s20, 32, s21
	s_min_i32 s22, s20, 8
	s_abs_i32 s20, s22
	s_sub_i32 s24, 0, s20
	s_and_b32 s5, s5, 0xffffff00
	s_sub_i32 s0, s0, s5
	s_abs_i32 s5, s0
	s_xor_b32 s23, s0, s22
	s_ashr_i32 s23, s23, 31
	s_mov_b32 s25, 0x1fffffc0
	s_mul_i32 s24, s24, s25
	s_mul_hi_u32 s24, s25, s24
	s_add_i32 s25, s25, s24
	s_mul_hi_u32 s24, s5, s25
	s_mul_i32 s25, s24, s20
	s_sub_i32 s5, s5, s25
	s_add_i32 s26, s24, 1
	s_sub_i32 s25, s5, s20
	s_cmp_ge_u32 s5, s20
	s_cselect_b32 s24, s26, s24
	s_cselect_b32 s5, s25, s5
	s_add_i32 s25, s24, 1
	s_cmp_ge_u32 s5, s20
	s_cselect_b32 s5, s25, s24
	s_xor_b32 s5, s5, s23
	s_sub_i32 s20, s5, s23
	s_mul_i32 s5, s20, s22
	s_sub_i32 s0, s0, s5
	s_add_i32 s22, s21, s0

.LBB0_1491:
	s_ashr_i32 s0, s0, 3
	s_add_i32 s0, s29, s0
	s_ashr_i32 s26, s0, 31
	s_lshr_b32 s26, s26, 25
	s_add_i32 s26, s0, s26
	s_ashr_i32 s27, s26, 7
	s_lshl_b32 s27, s27, 3
	s_sub_i32 s28, 32, s27
	s_min_i32 s28, s28, 8
	s_abs_i32 s29, s28
	s_sub_i32 s31, 0, s29
	s_and_b32 s26, s26, 0xffffff80
	s_sub_i32 s0, s0, s26
	s_abs_i32 s26, s0
	s_xor_b32 s30, s0, s28
	s_ashr_i32 s30, s30, 31
	s_mov_b32 s34, 0x1fffffc0
	s_mul_i32 s31, s31, s34
	s_mul_hi_u32 s31, s34, s31
	s_add_i32 s34, s34, s31
	s_mul_hi_u32 s31, s26, s34
	s_mul_i32 s34, s31, s29
	s_sub_i32 s26, s26, s34
	s_add_i32 s35, s31, 1
	s_sub_i32 s34, s26, s29
	s_cmp_ge_u32 s26, s29
	s_cselect_b32 s31, s35, s31
	s_cselect_b32 s26, s34, s26
	s_add_i32 s34, s31, 1
	s_cmp_ge_u32 s26, s29
	s_cselect_b32 s26, s34, s31
	s_xor_b32 s26, s26, s30
	s_sub_i32 s26, s26, s30
	s_mul_i32 s28, s26, s28
	s_sub_i32 s0, s0, s28
	s_add_i32 s28, s27, s0

.LBB0_1603:
	s_ashr_i32 s22, s24, 3
	s_add_i32 s22, s26, s22
	s_ashr_i32 s23, s22, 31
	s_lshr_b32 s23, s23, 23
	s_add_i32 s23, s22, s23
	s_ashr_i32 s24, s23, 9
	s_lshl_b32 s24, s24, 3
	s_sub_i32 s25, 32, s24
	s_min_i32 s25, s25, 8
	s_abs_i32 s26, s25
	s_sub_i32 s28, 0, s26
	s_and_b32 s23, s23, 0xfffffe00
	s_sub_i32 s23, s22, s23
	s_abs_i32 s22, s23
	s_xor_b32 s27, s23, s25
	s_ashr_i32 s27, s27, 31
	s_mov_b32 s29, 0x1fffffc0
	s_mul_i32 s28, s28, s29
	s_mul_hi_u32 s28, s29, s28
	s_add_i32 s29, s29, s28
	s_mul_hi_u32 s28, s22, s29
	s_mul_i32 s29, s28, s26
	s_sub_i32 s22, s22, s29
	s_add_i32 s38, s28, 1
	s_sub_i32 s29, s22, s26
	s_cmp_ge_u32 s22, s26
	s_cselect_b32 s28, s38, s28
	s_cselect_b32 s22, s29, s22
	s_add_i32 s29, s28, 1
	s_cmp_ge_u32 s22, s26
	s_cselect_b32 s22, s29, s28
	s_xor_b32 s22, s22, s27
	s_sub_i32 s22, s22, s27
	s_mul_i32 s25, s22, s25
	s_sub_i32 s23, s23, s25
	s_add_i32 s24, s24, s23

.LBB0_1679:
	s_ashr_i32 s12, s14, 3
	s_add_i32 s12, s16, s12
	s_ashr_i32 s13, s12, 31
	s_lshr_b32 s13, s13, 25
	s_add_i32 s13, s12, s13
	s_ashr_i32 s14, s13, 7
	s_lshl_b32 s14, s14, 3
	s_sub_i32 s15, 32, s14
	s_min_i32 s15, s15, 8
	s_abs_i32 s16, s15
	s_sub_i32 s18, 0, s16
	s_and_b32 s13, s13, 0xffffff80
	s_sub_i32 s13, s12, s13
	s_abs_i32 s12, s13
	s_xor_b32 s17, s13, s15
	s_ashr_i32 s17, s17, 31
	s_mov_b32 s19, 0x1fffffc0
	s_mul_i32 s18, s18, s19
	s_mul_hi_u32 s18, s19, s18
	s_add_i32 s19, s19, s18
	s_mul_hi_u32 s18, s12, s19
	s_mul_i32 s19, s18, s16
	s_sub_i32 s12, s12, s19
	s_add_i32 s26, s18, 1
	s_sub_i32 s19, s12, s16
	s_cmp_ge_u32 s12, s16
	s_cselect_b32 s18, s26, s18
	s_cselect_b32 s12, s19, s12
	s_add_i32 s19, s18, 1
	s_cmp_ge_u32 s12, s16
	s_cselect_b32 s12, s19, s18
	s_xor_b32 s12, s12, s17
	s_sub_i32 s12, s12, s17
	s_mul_i32 s15, s12, s15
	s_sub_i32 s13, s13, s15
	s_add_i32 s14, s14, s13
